# v15 plus: all FFN conversion tiles in phase F (none in E), and unified hand-written phase-A weight transposer
# baseline (speedup 1.0000x reference)
; #define LAS __attribute__((address_space(3)))
; __device__ __forceinline__ int tid_l() { int t = threadIdx.x; asm volatile("" : "+v"(t)); return t; }
; template <class SEL, class CTX>
; __device__ __forceinline__ void transpose_run(LAS unsigned char* lds, const CTX& ctx, int t0, int t1, int stride) {
;     const int tid = tid_l();
;     LAS unsigned* tl = (LAS unsigned*)lds;
;     const int k = tid >> 3, n8 = (tid & 7) * 8;
;     f32x4 v[4][2];
;     TrDesc d; int lt;
;     if (t0 < t1) { SEL::get(ctx, t0, d, lt); const int nkt = d.K >> 6, kt = lt % nkt, ct = lt / nkt;
;         const float* s = d.src + (size_t)(kt * 64 + k) * d.ldsrc + d.c0 + ct * 256 + n8;
; #pragma unroll
;         for (int q = 0; q < 4; ++q) { v[q][0] = *(const f32x4*)(s + q * 64); v[q][1] = *(const f32x4*)(s + q * 64 + 4); } }
;     for (int t = t0; t < t1; t += stride) {
;         SEL::get(ctx, t, d, lt);
;         const int nkt = d.K >> 6, kt = lt % nkt, ct = lt / nkt;
;         unsigned w[4][4];
; #pragma unroll
;         for (int q = 0; q < 4; ++q)
; #pragma unroll
;             for (int j = 0; j < 4; ++j) { const float lo = v[q][0][j], hi = v[q][1][j];
;                 const float recv = __shfl_xor((k & 1) ? lo : hi, 8);
;                 w[q][j] = (k & 1) ? cvt_pk_bf16(recv, hi) : cvt_pk_bf16(lo, recv); }
;         if (t + stride < t1) { TrDesc dn; int ltn; SEL::get(ctx, t + stride, dn, ltn); const int nktn = dn.K >> 6, ktn = ltn % nktn, ctn = ltn / nktn;
;             const float* s = dn.src + (size_t)(ktn * 64 + k) * dn.ldsrc + dn.c0 + ctn * 256 + n8;
; #pragma unroll
;             for (int q = 0; q < 4; ++q) { v[q][0] = *(const f32x4*)(s + q * 64); v[q][1] = *(const f32x4*)(s + q * 64 + 4); } }
; __global__ void __launch_bounds__(NTHREADS, 2) mega_fwd(Args a) {
;     ...
;                 const TrDesc td[4] = {
;                     {a.in[3] + (size_t)l * 2048 * INW, INW, 2048, 0, 1536, WINAC, 0, 0},
;                     {a.in[3] + (size_t)l * 2048 * INW, INW, 2048, 2048, 768, WINAC, 0, 1536},
;                     {a.in[18] + (size_t)l * 2048 * 2048, 2048, 2048, 0, 2048, WOUT, 0, 0},
;                     {a.in[15] + (size_t)l * 768 * 768, 768, 768, 0, 768, WGLU, 0, 0}};
;                 const int ntile[4] = {32 * 6, 32 * 3, 32 * 8, 12 * 3};
; #pragma unroll
;                 for (int m = 0; m < 4; ++m) transpose_run<SelOne>(lds, td[m], bx, ntile[m], G);
.LBB0_81:
	s_or_b64 exec, exec, s[28:29]
	v_writelane_b32 v255, s0, 24
	v_writelane_b32 v255, s2, 25
	v_writelane_b32 v255, s28, 26
	v_writelane_b32 v255, s29, 27
	v_writelane_b32 v255, s33, 28
	v_writelane_b32 v255, s34, 29
	v_writelane_b32 v255, s35, 30
	v_writelane_b32 v255, s36, 31
	v_writelane_b32 v255, s37, 32
	v_writelane_b32 v255, s38, 33
	v_writelane_b32 v255, s39, 34
	v_writelane_b32 v255, s40, 35
	v_writelane_b32 v255, s41, 36
	v_writelane_b32 v255, s44, 37
	v_writelane_b32 v255, s45, 38
	v_writelane_b32 v255, s46, 39
	v_writelane_b32 v255, s47, 44
	v_writelane_b32 v255, s48, 45
	v_writelane_b32 v255, s49, 46
	v_writelane_b32 v255, s50, 47
	v_writelane_b32 v255, s51, 48
	v_writelane_b32 v255, s52, 49
	v_writelane_b32 v255, s53, 50
	v_writelane_b32 v255, s54, 51
	v_writelane_b32 v255, s55, 52
	v_writelane_b32 v255, s56, 53
	v_writelane_b32 v255, s57, 54
	v_writelane_b32 v255, s58, 55
	v_writelane_b32 v255, s59, 56
	v_writelane_b32 v255, s90, 57
	v_writelane_b32 v255, vcc_lo, 58
	v_writelane_b32 v255, vcc_hi, 59
	s_mov_b32 s0, s48
	s_mov_b32 s2, s42
	v_readlane_b32 s44, v253, 10
	v_readlane_b32 s45, v253, 11
	v_readlane_b32 s46, v253, 24
	v_readlane_b32 s47, v253, 25
	v_readlane_b32 s48, v255, 11
	v_readlane_b32 s49, v255, 12
	s_nop 3
	s_mul_i32 s28, s30, 0x1600000
	s_add_u32 s44, s44, s28
	s_addc_u32 s45, s45, 0
	s_mul_i32 s28, s30, 0x1000000
	s_add_u32 s46, s46, s28
	s_addc_u32 s47, s47, 0
	s_mul_i32 s28, s30, 0x240000
	s_add_u32 s48, s48, s28
	s_addc_u32 s49, s49, 0
	s_mov_b64 s[50:51], s[22:23]
	s_add_u32 s52, s22, 0xd00000
	s_addc_u32 s53, s23, 0
	v_lshrrev_b32_e32 v100, 3, v175
	v_and_b32_e32 v96, 7, v175
	v_lshlrev_b32_e32 v101, 5, v96
	v_and_b32_e32 v97, 1, v100
	v_cmp_ne_u32_e32 vcc, 0, v97
	v_lshlrev_b32_e32 v98, 3, v96
	v_lshl_add_u32 v98, v97, 2, v98
	v_mul_u32_u24_e32 v98, 33, v98
	v_lshrrev_b32_e32 v99, 1, v100
	v_add_u32_e32 v98, v98, v99
	v_lshlrev_b32_e32 v102, 2, v98
	v_mul_u32_u24_e32 v98, 33, v100
	v_lshl_add_u32 v98, v96, 2, v98
	v_lshlrev_b32_e32 v103, 2, v98
	v_lshlrev_b32_e32 v99, 4, v96
	v_lshl_add_u32 v104, v100, 12, v99
	v_mul_u32_u24_e32 v98, 0x600, v100
	v_add_u32_e32 v105, v98, v99
	s_cmp_ge_u32 s0, 580
	s_cbranch_scc1 .Latr_done
	s_mov_b32 s33, s0
	s_cmpk_ge_u32 s33, 0x220
	s_cselect_b32 s34, 1, 0
	s_cmpk_ge_u32 s33, 0x120
	s_cselect_b32 s35, 1, 0
	s_cmpk_ge_u32 s33, 0xc0
	s_cselect_b32 s41, 1, 0
	s_mul_i32 s36, s41, 0xc0
	s_mul_i32 s39, s35, 0x60
	s_add_i32 s36, s36, s39
	s_lshl_b32 s39, s34, 8
	s_add_i32 s36, s36, s39
	s_sub_i32 s36, s33, s36
	s_sub_i32 s41, s41, s35
	s_mul_hi_u32 s37, s36, 0x15555556
	s_mul_i32 s38, s37, 12
	s_sub_i32 s38, s36, s38
	s_lshr_b32 s39, s36, 5
	s_and_b32 s40, s36, 31
	s_cmp_eq_u32 s34, 1
	s_cselect_b32 s37, s37, s39
	s_cselect_b32 s38, s38, s40
	s_mov_b32 s58, 0x2c00
	s_cselect_b32 s58, 0xc00, s58
	s_cselect_b32 s54, s48, s44
	s_cselect_b32 s55, s49, s45
	s_sub_i32 s39, s35, s34
	s_cmp_eq_u32 s39, 1
	s_cselect_b32 s58, 0x2000, s58
	s_cselect_b32 s54, s46, s54
	s_cselect_b32 s55, s47, s55
	s_lshl_b32 s39, s38, 6
	s_mul_i32 s39, s39, s58
	s_lshl_b32 s40, s37, 10
	s_add_u32 s39, s39, s40
	s_lshl_b32 s40, s41, 13
	s_add_u32 s39, s39, s40
	s_add_u32 s54, s54, s39
	s_addc_u32 s55, s55, 0
	v_mad_u32_u24 v106, v100, s58, v101
	global_load_dwordx4 v[0:3], v106, s[54:55]
	global_load_dwordx4 v[4:7], v106, s[54:55] offset:16
	global_load_dwordx4 v[8:11], v106, s[54:55] offset:256
	global_load_dwordx4 v[12:15], v106, s[54:55] offset:272
	global_load_dwordx4 v[16:19], v106, s[54:55] offset:512
	global_load_dwordx4 v[20:23], v106, s[54:55] offset:528
	global_load_dwordx4 v[24:27], v106, s[54:55] offset:768
	global_load_dwordx4 v[28:31], v106, s[54:55] offset:784
.Latr_loop:
	s_add_i32 s33, s0, s2
	s_cmp_lt_u32 s33, 580
	s_cselect_b32 s33, s33, s0
	s_cmpk_ge_u32 s33, 0x220
	s_cselect_b32 s34, 1, 0
	s_cmpk_ge_u32 s33, 0x120
	s_cselect_b32 s35, 1, 0
	s_cmpk_ge_u32 s33, 0xc0
	s_cselect_b32 s41, 1, 0
	s_mul_i32 s36, s41, 0xc0
	s_mul_i32 s39, s35, 0x60
	s_add_i32 s36, s36, s39
	s_lshl_b32 s39, s34, 8
	s_add_i32 s36, s36, s39
	s_sub_i32 s36, s33, s36
	s_sub_i32 s41, s41, s35
	s_mul_hi_u32 s37, s36, 0x15555556
	s_mul_i32 s38, s37, 12
	s_sub_i32 s38, s36, s38
	s_lshr_b32 s39, s36, 5
	s_and_b32 s40, s36, 31
	s_cmp_eq_u32 s34, 1
	s_cselect_b32 s37, s37, s39
	s_cselect_b32 s38, s38, s40
	s_mov_b32 s58, 0x2c00
	s_cselect_b32 s58, 0xc00, s58
	s_cselect_b32 s54, s48, s44
	s_cselect_b32 s55, s49, s45
	s_sub_i32 s39, s35, s34
	s_cmp_eq_u32 s39, 1
	s_cselect_b32 s58, 0x2000, s58
	s_cselect_b32 s54, s46, s54
	s_cselect_b32 s55, s47, s55
	s_lshl_b32 s39, s38, 6
	s_mul_i32 s39, s39, s58
	s_lshl_b32 s40, s37, 10
	s_add_u32 s39, s39, s40
	s_lshl_b32 s40, s41, 13
	s_add_u32 s39, s39, s40
	s_add_u32 s54, s54, s39
	s_addc_u32 s55, s55, 0
	v_mad_u32_u24 v106, v100, s58, v101
	global_load_dwordx4 v[32:35], v106, s[54:55]
	global_load_dwordx4 v[36:39], v106, s[54:55] offset:16
	global_load_dwordx4 v[40:43], v106, s[54:55] offset:256
	global_load_dwordx4 v[44:47], v106, s[54:55] offset:272
	global_load_dwordx4 v[48:51], v106, s[54:55] offset:512
	global_load_dwordx4 v[52:55], v106, s[54:55] offset:528
	global_load_dwordx4 v[56:59], v106, s[54:55] offset:768
	global_load_dwordx4 v[60:63], v106, s[54:55] offset:784
	s_waitcnt vmcnt(8)
; #define LAS __attribute__((address_space(3)))
; __device__ __forceinline__ unsigned cvt_pk_bf16(float lo, float hi) { unsigned r; asm("v_cvt_pk_bf16_f32 %0, %1, %2" : "=v"(r) : "v"(lo), "v"(hi)); return r; }
; template <class SEL, class CTX>
; __device__ __forceinline__ void transpose_run(LAS unsigned char* lds, const CTX& ctx, int t0, int t1, int stride) {
;     ...
;         for (int q = 0; q < 4; ++q)
; #pragma unroll
;             for (int j = 0; j < 4; ++j) { const float lo = v[q][0][j], hi = v[q][1][j];
;                 const float recv = __shfl_xor((k & 1) ? lo : hi, 8);
;                 w[q][j] = (k & 1) ? cvt_pk_bf16(recv, hi) : cvt_pk_bf16(lo, recv); }
;         if (t + stride < t1) { TrDesc dn; int ltn; SEL::get(ctx, t + stride, dn, ltn); const int nktn = dn.K >> 6, ktn = ltn % nktn, ctn = ltn / nktn;
;             const float* s = dn.src + (size_t)(ktn * 64 + k) * dn.ldsrc + dn.c0 + ctn * 256 + n8;
; #pragma unroll
;             for (int q = 0; q < 4; ++q) { v[q][0] = *(const f32x4*)(s + q * 64); v[q][1] = *(const f32x4*)(s + q * 64 + 4); } }
; #pragma unroll
;         for (int q = 0; q < 4; ++q)
; #pragma unroll
;             for (int j = 0; j < 4; ++j) tl[(q * 64 + n8 + j + ((k & 1) ? 4 : 0)) * 33 + (k >> 1)] = w[q][j];
;         __syncthreads();
;         { const int n = tid >> 3, k8 = (tid & 7) * 8;
; #pragma unroll
;           for (int q = 0; q < 4; ++q) {
;               const LAS unsigned* p = tl + (q * 64 + n) * 33 + (k8 >> 1);
;               u32x4 ww; ww.x = p[0]; ww.y = p[1]; ww.z = p[2]; ww.w = p[3];
;               const int cc = ct * 256 + q * 64 + n;
;               const int drow = d.mode == 0 ? d.doff + cc : ((cc >> 7) * 256 + (cc & 127) + (d.mode == 2 ? 128 : 0));
;               *(u32x4*)(d.dst + (size_t)drow * d.K + kt * 64 + k8) = ww; } }
	v_mov_b32_dpp v64, v0 row_ror:8 row_mask:0xf bank_mask:0xf
	v_mov_b32_dpp v65, v4 row_ror:8 row_mask:0xf bank_mask:0xf
	v_cvt_pk_bf16_f32 v66, v0, v64
	v_cvt_pk_bf16_f32 v67, v65, v4
	v_cndmask_b32_e32 v66, v66, v67, vcc
	ds_write_b32 v102, v66 offset:0
	v_mov_b32_dpp v68, v1 row_ror:8 row_mask:0xf bank_mask:0xf
	v_mov_b32_dpp v69, v5 row_ror:8 row_mask:0xf bank_mask:0xf
	v_cvt_pk_bf16_f32 v70, v1, v68
	v_cvt_pk_bf16_f32 v71, v69, v5
	v_cndmask_b32_e32 v70, v70, v71, vcc
	ds_write_b32 v102, v70 offset:132
	v_mov_b32_dpp v72, v2 row_ror:8 row_mask:0xf bank_mask:0xf
	v_mov_b32_dpp v73, v6 row_ror:8 row_mask:0xf bank_mask:0xf
	v_cvt_pk_bf16_f32 v74, v2, v72
	v_cvt_pk_bf16_f32 v75, v73, v6
	v_cndmask_b32_e32 v74, v74, v75, vcc
	ds_write_b32 v102, v74 offset:264
	v_mov_b32_dpp v76, v3 row_ror:8 row_mask:0xf bank_mask:0xf
	v_mov_b32_dpp v77, v7 row_ror:8 row_mask:0xf bank_mask:0xf
	v_cvt_pk_bf16_f32 v78, v3, v76
	v_cvt_pk_bf16_f32 v79, v77, v7
	v_cndmask_b32_e32 v78, v78, v79, vcc
	ds_write_b32 v102, v78 offset:396
	v_mov_b32_dpp v64, v8 row_ror:8 row_mask:0xf bank_mask:0xf
	v_mov_b32_dpp v65, v12 row_ror:8 row_mask:0xf bank_mask:0xf
	v_cvt_pk_bf16_f32 v66, v8, v64
	v_cvt_pk_bf16_f32 v67, v65, v12
	v_cndmask_b32_e32 v66, v66, v67, vcc
	ds_write_b32 v102, v66 offset:8448
	v_mov_b32_dpp v68, v9 row_ror:8 row_mask:0xf bank_mask:0xf
	v_mov_b32_dpp v69, v13 row_ror:8 row_mask:0xf bank_mask:0xf
	v_cvt_pk_bf16_f32 v70, v9, v68
	v_cvt_pk_bf16_f32 v71, v69, v13
	v_cndmask_b32_e32 v70, v70, v71, vcc
	ds_write_b32 v102, v70 offset:8580
	v_mov_b32_dpp v72, v10 row_ror:8 row_mask:0xf bank_mask:0xf
	v_mov_b32_dpp v73, v14 row_ror:8 row_mask:0xf bank_mask:0xf
	v_cvt_pk_bf16_f32 v74, v10, v72
	v_cvt_pk_bf16_f32 v75, v73, v14
	v_cndmask_b32_e32 v74, v74, v75, vcc
	ds_write_b32 v102, v74 offset:8712
	v_mov_b32_dpp v76, v11 row_ror:8 row_mask:0xf bank_mask:0xf
	v_mov_b32_dpp v77, v15 row_ror:8 row_mask:0xf bank_mask:0xf
	v_cvt_pk_bf16_f32 v78, v11, v76
	v_cvt_pk_bf16_f32 v79, v77, v15
	v_cndmask_b32_e32 v78, v78, v79, vcc
	ds_write_b32 v102, v78 offset:8844
	v_mov_b32_dpp v64, v16 row_ror:8 row_mask:0xf bank_mask:0xf
	v_mov_b32_dpp v65, v20 row_ror:8 row_mask:0xf bank_mask:0xf
	v_cvt_pk_bf16_f32 v66, v16, v64
	v_cvt_pk_bf16_f32 v67, v65, v20
	v_cndmask_b32_e32 v66, v66, v67, vcc
	ds_write_b32 v102, v66 offset:16896
	v_mov_b32_dpp v68, v17 row_ror:8 row_mask:0xf bank_mask:0xf
	v_mov_b32_dpp v69, v21 row_ror:8 row_mask:0xf bank_mask:0xf
	v_cvt_pk_bf16_f32 v70, v17, v68
	v_cvt_pk_bf16_f32 v71, v69, v21
	v_cndmask_b32_e32 v70, v70, v71, vcc
	ds_write_b32 v102, v70 offset:17028
	v_mov_b32_dpp v72, v18 row_ror:8 row_mask:0xf bank_mask:0xf
	v_mov_b32_dpp v73, v22 row_ror:8 row_mask:0xf bank_mask:0xf
	v_cvt_pk_bf16_f32 v74, v18, v72
	v_cvt_pk_bf16_f32 v75, v73, v22
	v_cndmask_b32_e32 v74, v74, v75, vcc
	ds_write_b32 v102, v74 offset:17160
	v_mov_b32_dpp v76, v19 row_ror:8 row_mask:0xf bank_mask:0xf
	v_mov_b32_dpp v77, v23 row_ror:8 row_mask:0xf bank_mask:0xf
	v_cvt_pk_bf16_f32 v78, v19, v76
	v_cvt_pk_bf16_f32 v79, v77, v23
	v_cndmask_b32_e32 v78, v78, v79, vcc
	ds_write_b32 v102, v78 offset:17292
	v_mov_b32_dpp v64, v24 row_ror:8 row_mask:0xf bank_mask:0xf
	v_mov_b32_dpp v65, v28 row_ror:8 row_mask:0xf bank_mask:0xf
	v_cvt_pk_bf16_f32 v66, v24, v64
	v_cvt_pk_bf16_f32 v67, v65, v28
	v_cndmask_b32_e32 v66, v66, v67, vcc
	ds_write_b32 v102, v66 offset:25344
	v_mov_b32_dpp v68, v25 row_ror:8 row_mask:0xf bank_mask:0xf
	v_mov_b32_dpp v69, v29 row_ror:8 row_mask:0xf bank_mask:0xf
	v_cvt_pk_bf16_f32 v70, v25, v68
	v_cvt_pk_bf16_f32 v71, v69, v29
	v_cndmask_b32_e32 v70, v70, v71, vcc
	ds_write_b32 v102, v70 offset:25476
	v_mov_b32_dpp v72, v26 row_ror:8 row_mask:0xf bank_mask:0xf
	v_mov_b32_dpp v73, v30 row_ror:8 row_mask:0xf bank_mask:0xf
	v_cvt_pk_bf16_f32 v74, v26, v72
	v_cvt_pk_bf16_f32 v75, v73, v30
	v_cndmask_b32_e32 v74, v74, v75, vcc
	ds_write_b32 v102, v74 offset:25608
	v_mov_b32_dpp v76, v27 row_ror:8 row_mask:0xf bank_mask:0xf
	v_mov_b32_dpp v77, v31 row_ror:8 row_mask:0xf bank_mask:0xf
	v_cvt_pk_bf16_f32 v78, v27, v76
	v_cvt_pk_bf16_f32 v79, v77, v31
	v_cndmask_b32_e32 v78, v78, v79, vcc
	ds_write_b32 v102, v78 offset:25740
	s_waitcnt lgkmcnt(0)
	s_barrier
	s_cmpk_ge_u32 s0, 0x220
	s_cselect_b32 s34, 1, 0
	s_cmpk_ge_u32 s0, 0x120
	s_cselect_b32 s35, 1, 0
	s_cmpk_ge_u32 s0, 0xc0
	s_cselect_b32 s41, 1, 0
	s_mul_i32 s36, s41, 0xc0
	s_mul_i32 s39, s35, 0x60
	s_add_i32 s36, s36, s39
	s_lshl_b32 s39, s34, 8
	s_add_i32 s36, s36, s39
	s_sub_i32 s36, s0, s36
	s_sub_i32 s41, s41, s35
	s_mul_hi_u32 s37, s36, 0x15555556
	s_mul_i32 s38, s37, 12
	s_sub_i32 s38, s36, s38
	s_lshr_b32 s39, s36, 5
	s_and_b32 s40, s36, 31
	s_cmp_eq_u32 s34, 1
	s_cselect_b32 s37, s37, s39
	s_cselect_b32 s38, s38, s40
	s_mov_b32 s59, 0x40000
	s_cselect_b32 s59, 0x18000, s59
	s_mov_b32 s90, 0x80000
	s_cselect_b32 s90, 0x30000, s90
	s_mov_b32 s33, 0xc0000
	s_cselect_b32 s33, 0x48000, s33
	s_mov_b32 s39, 0x1000
	s_cselect_b32 s39, 0x600, s39
	s_cselect_b64 s[28:29], -1, 0
	s_add_u32 s56, s22, 0x1500000
	s_addc_u32 s57, s23, 0
	s_cmp_eq_u32 s34, 1
	s_cselect_b32 s56, s56, s50
	s_cselect_b32 s57, s57, s51
	s_sub_i32 s40, s35, s34
	s_cmp_eq_u32 s40, 1
	s_cselect_b32 s56, s52, s56
	s_cselect_b32 s57, s53, s57
	s_lshl_b32 s40, s37, 8
	s_mul_i32 s36, s41, 0x600
	s_add_i32 s40, s40, s36
	s_mul_i32 s40, s40, s39
	s_lshl_b32 s36, s38, 7
	s_add_u32 s40, s40, s36
	s_add_u32 s56, s56, s40
	s_addc_u32 s57, s57, 0
	v_cndmask_b32_e64 v107, v104, v105, s[28:29]
	v_add_u32_e32 v108, s59, v107
	v_add_u32_e32 v109, s90, v107
	v_add_u32_e32 v110, s33, v107
	ds_read_b32 v80, v103 offset:0
	ds_read_b32 v81, v103 offset:4
	ds_read_b32 v82, v103 offset:8
	ds_read_b32 v83, v103 offset:12
	ds_read_b32 v84, v103 offset:8448
	ds_read_b32 v85, v103 offset:8452
	ds_read_b32 v86, v103 offset:8456
	ds_read_b32 v87, v103 offset:8460
	ds_read_b32 v88, v103 offset:16896
	ds_read_b32 v89, v103 offset:16900
	ds_read_b32 v90, v103 offset:16904
	ds_read_b32 v91, v103 offset:16908
	ds_read_b32 v92, v103 offset:25344
	ds_read_b32 v93, v103 offset:25348
	ds_read_b32 v94, v103 offset:25352
	ds_read_b32 v95, v103 offset:25356
	s_waitcnt lgkmcnt(0)
	global_store_dwordx4 v107, v[80:83], s[56:57]
	global_store_dwordx4 v108, v[84:87], s[56:57]
	global_store_dwordx4 v109, v[88:91], s[56:57]
	global_store_dwordx4 v110, v[92:95], s[56:57]
	s_add_i32 s0, s0, s2
	s_cmp_ge_u32 s0, 580
	s_cbranch_scc1 .Latr_done
; __device__ __forceinline__ unsigned cvt_pk_bf16(float lo, float hi) { unsigned r; asm("v_cvt_pk_bf16_f32 %0, %1, %2" : "=v"(r) : "v"(lo), "v"(hi)); return r; }
; template <class SEL, class CTX>
; __device__ __forceinline__ void transpose_run(LAS unsigned char* lds, const CTX& ctx, int t0, int t1, int stride) {
;     ...
;     for (int t = t0; t < t1; t += stride) {
;         SEL::get(ctx, t, d, lt);
;         const int nkt = d.K >> 6, kt = lt % nkt, ct = lt / nkt;
;         unsigned w[4][4];
; #pragma unroll
;         for (int q = 0; q < 4; ++q)
; #pragma unroll
;             for (int j = 0; j < 4; ++j) { const float lo = v[q][0][j], hi = v[q][1][j];
;                 const float recv = __shfl_xor((k & 1) ? lo : hi, 8);
;                 w[q][j] = (k & 1) ? cvt_pk_bf16(recv, hi) : cvt_pk_bf16(lo, recv); }
;         if (t + stride < t1) { TrDesc dn; int ltn; SEL::get(ctx, t + stride, dn, ltn); const int nktn = dn.K >> 6, ktn = ltn % nktn, ctn = ltn / nktn;
;             const float* s = dn.src + (size_t)(ktn * 64 + k) * dn.ldsrc + dn.c0 + ctn * 256 + n8;
; #pragma unroll
;             for (int q = 0; q < 4; ++q) { v[q][0] = *(const f32x4*)(s + q * 64); v[q][1] = *(const f32x4*)(s + q * 64 + 4); } }
; #pragma unroll
;         for (int q = 0; q < 4; ++q)
; #pragma unroll
;             for (int j = 0; j < 4; ++j) tl[(q * 64 + n8 + j + ((k & 1) ? 4 : 0)) * 33 + (k >> 1)] = w[q][j];
	s_add_i32 s33, s0, s2
	s_cmp_lt_u32 s33, 580
	s_cselect_b32 s33, s33, s0
	s_cmpk_ge_u32 s33, 0x220
	s_cselect_b32 s34, 1, 0
	s_cmpk_ge_u32 s33, 0x120
	s_cselect_b32 s35, 1, 0
	s_cmpk_ge_u32 s33, 0xc0
	s_cselect_b32 s41, 1, 0
	s_mul_i32 s36, s41, 0xc0
	s_mul_i32 s39, s35, 0x60
	s_add_i32 s36, s36, s39
	s_lshl_b32 s39, s34, 8
	s_add_i32 s36, s36, s39
	s_sub_i32 s36, s33, s36
	s_sub_i32 s41, s41, s35
	s_mul_hi_u32 s37, s36, 0x15555556
	s_mul_i32 s38, s37, 12
	s_sub_i32 s38, s36, s38
	s_lshr_b32 s39, s36, 5
	s_and_b32 s40, s36, 31
	s_cmp_eq_u32 s34, 1
	s_cselect_b32 s37, s37, s39
	s_cselect_b32 s38, s38, s40
	s_mov_b32 s58, 0x2c00
	s_cselect_b32 s58, 0xc00, s58
	s_cselect_b32 s54, s48, s44
	s_cselect_b32 s55, s49, s45
	s_sub_i32 s39, s35, s34
	s_cmp_eq_u32 s39, 1
	s_cselect_b32 s58, 0x2000, s58
	s_cselect_b32 s54, s46, s54
	s_cselect_b32 s55, s47, s55
	s_lshl_b32 s39, s38, 6
	s_mul_i32 s39, s39, s58
	s_lshl_b32 s40, s37, 10
	s_add_u32 s39, s39, s40
	s_lshl_b32 s40, s41, 13
	s_add_u32 s39, s39, s40
	s_add_u32 s54, s54, s39
	s_addc_u32 s55, s55, 0
	v_mad_u32_u24 v106, v100, s58, v101
	global_load_dwordx4 v[0:3], v106, s[54:55]
	global_load_dwordx4 v[4:7], v106, s[54:55] offset:16
	global_load_dwordx4 v[8:11], v106, s[54:55] offset:256
	global_load_dwordx4 v[12:15], v106, s[54:55] offset:272
	global_load_dwordx4 v[16:19], v106, s[54:55] offset:512
	global_load_dwordx4 v[20:23], v106, s[54:55] offset:528
	global_load_dwordx4 v[24:27], v106, s[54:55] offset:768
	global_load_dwordx4 v[28:31], v106, s[54:55] offset:784
	s_waitcnt vmcnt(8)
	v_mov_b32_dpp v64, v32 row_ror:8 row_mask:0xf bank_mask:0xf
	v_mov_b32_dpp v65, v36 row_ror:8 row_mask:0xf bank_mask:0xf
	v_cvt_pk_bf16_f32 v66, v32, v64
	v_cvt_pk_bf16_f32 v67, v65, v36
	v_cndmask_b32_e32 v66, v66, v67, vcc
	ds_write_b32 v102, v66 offset:33792
	v_mov_b32_dpp v68, v33 row_ror:8 row_mask:0xf bank_mask:0xf
	v_mov_b32_dpp v69, v37 row_ror:8 row_mask:0xf bank_mask:0xf
	v_cvt_pk_bf16_f32 v70, v33, v68
	v_cvt_pk_bf16_f32 v71, v69, v37
	v_cndmask_b32_e32 v70, v70, v71, vcc
	ds_write_b32 v102, v70 offset:33924
	v_mov_b32_dpp v72, v34 row_ror:8 row_mask:0xf bank_mask:0xf
	v_mov_b32_dpp v73, v38 row_ror:8 row_mask:0xf bank_mask:0xf
	v_cvt_pk_bf16_f32 v74, v34, v72
	v_cvt_pk_bf16_f32 v75, v73, v38
	v_cndmask_b32_e32 v74, v74, v75, vcc
	ds_write_b32 v102, v74 offset:34056
	v_mov_b32_dpp v76, v35 row_ror:8 row_mask:0xf bank_mask:0xf
	v_mov_b32_dpp v77, v39 row_ror:8 row_mask:0xf bank_mask:0xf
	v_cvt_pk_bf16_f32 v78, v35, v76
	v_cvt_pk_bf16_f32 v79, v77, v39
	v_cndmask_b32_e32 v78, v78, v79, vcc
	ds_write_b32 v102, v78 offset:34188
	v_mov_b32_dpp v64, v40 row_ror:8 row_mask:0xf bank_mask:0xf
	v_mov_b32_dpp v65, v44 row_ror:8 row_mask:0xf bank_mask:0xf
	v_cvt_pk_bf16_f32 v66, v40, v64
	v_cvt_pk_bf16_f32 v67, v65, v44
	v_cndmask_b32_e32 v66, v66, v67, vcc
	ds_write_b32 v102, v66 offset:42240
	v_mov_b32_dpp v68, v41 row_ror:8 row_mask:0xf bank_mask:0xf
	v_mov_b32_dpp v69, v45 row_ror:8 row_mask:0xf bank_mask:0xf
	v_cvt_pk_bf16_f32 v70, v41, v68
	v_cvt_pk_bf16_f32 v71, v69, v45
	v_cndmask_b32_e32 v70, v70, v71, vcc
	ds_write_b32 v102, v70 offset:42372
	v_mov_b32_dpp v72, v42 row_ror:8 row_mask:0xf bank_mask:0xf
	v_mov_b32_dpp v73, v46 row_ror:8 row_mask:0xf bank_mask:0xf
	v_cvt_pk_bf16_f32 v74, v42, v72
	v_cvt_pk_bf16_f32 v75, v73, v46
	v_cndmask_b32_e32 v74, v74, v75, vcc
	ds_write_b32 v102, v74 offset:42504
	v_mov_b32_dpp v76, v43 row_ror:8 row_mask:0xf bank_mask:0xf
	v_mov_b32_dpp v77, v47 row_ror:8 row_mask:0xf bank_mask:0xf
	v_cvt_pk_bf16_f32 v78, v43, v76
	v_cvt_pk_bf16_f32 v79, v77, v47
	v_cndmask_b32_e32 v78, v78, v79, vcc
	ds_write_b32 v102, v78 offset:42636
	v_mov_b32_dpp v64, v48 row_ror:8 row_mask:0xf bank_mask:0xf
	v_mov_b32_dpp v65, v52 row_ror:8 row_mask:0xf bank_mask:0xf
	v_cvt_pk_bf16_f32 v66, v48, v64
	v_cvt_pk_bf16_f32 v67, v65, v52
	v_cndmask_b32_e32 v66, v66, v67, vcc
	ds_write_b32 v102, v66 offset:50688
	v_mov_b32_dpp v68, v49 row_ror:8 row_mask:0xf bank_mask:0xf
	v_mov_b32_dpp v69, v53 row_ror:8 row_mask:0xf bank_mask:0xf
	v_cvt_pk_bf16_f32 v70, v49, v68
	v_cvt_pk_bf16_f32 v71, v69, v53
	v_cndmask_b32_e32 v70, v70, v71, vcc
	ds_write_b32 v102, v70 offset:50820
	v_mov_b32_dpp v72, v50 row_ror:8 row_mask:0xf bank_mask:0xf
	v_mov_b32_dpp v73, v54 row_ror:8 row_mask:0xf bank_mask:0xf
	v_cvt_pk_bf16_f32 v74, v50, v72
	v_cvt_pk_bf16_f32 v75, v73, v54
	v_cndmask_b32_e32 v74, v74, v75, vcc
	ds_write_b32 v102, v74 offset:50952
	v_mov_b32_dpp v76, v51 row_ror:8 row_mask:0xf bank_mask:0xf
	v_mov_b32_dpp v77, v55 row_ror:8 row_mask:0xf bank_mask:0xf
	v_cvt_pk_bf16_f32 v78, v51, v76
	v_cvt_pk_bf16_f32 v79, v77, v55
	v_cndmask_b32_e32 v78, v78, v79, vcc
	ds_write_b32 v102, v78 offset:51084
	v_mov_b32_dpp v64, v56 row_ror:8 row_mask:0xf bank_mask:0xf
	v_mov_b32_dpp v65, v60 row_ror:8 row_mask:0xf bank_mask:0xf
	v_cvt_pk_bf16_f32 v66, v56, v64
	v_cvt_pk_bf16_f32 v67, v65, v60
	v_cndmask_b32_e32 v66, v66, v67, vcc
	ds_write_b32 v102, v66 offset:59136
	v_mov_b32_dpp v68, v57 row_ror:8 row_mask:0xf bank_mask:0xf
	v_mov_b32_dpp v69, v61 row_ror:8 row_mask:0xf bank_mask:0xf
	v_cvt_pk_bf16_f32 v70, v57, v68
	v_cvt_pk_bf16_f32 v71, v69, v61
	v_cndmask_b32_e32 v70, v70, v71, vcc
	ds_write_b32 v102, v70 offset:59268
	v_mov_b32_dpp v72, v58 row_ror:8 row_mask:0xf bank_mask:0xf
	v_mov_b32_dpp v73, v62 row_ror:8 row_mask:0xf bank_mask:0xf
	v_cvt_pk_bf16_f32 v74, v58, v72
	v_cvt_pk_bf16_f32 v75, v73, v62
	v_cndmask_b32_e32 v74, v74, v75, vcc
	ds_write_b32 v102, v74 offset:59400
	v_mov_b32_dpp v76, v59 row_ror:8 row_mask:0xf bank_mask:0xf
	v_mov_b32_dpp v77, v63 row_ror:8 row_mask:0xf bank_mask:0xf
	v_cvt_pk_bf16_f32 v78, v59, v76
	v_cvt_pk_bf16_f32 v79, v77, v63
	v_cndmask_b32_e32 v78, v78, v79, vcc
	ds_write_b32 v102, v78 offset:59532
	s_waitcnt lgkmcnt(0)
	s_barrier
; #define LAS __attribute__((address_space(3)))
; template <class SEL, class CTX>
; __device__ __forceinline__ void transpose_run(LAS unsigned char* lds, const CTX& ctx, int t0, int t1, int stride) {
;     ...
;     if (t0 < t1) { SEL::get(ctx, t0, d, lt); const int nkt = d.K >> 6, kt = lt % nkt, ct = lt / nkt;
;         const float* s = d.src + (size_t)(kt * 64 + k) * d.ldsrc + d.c0 + ct * 256 + n8;
; #pragma unroll
;         for (int q = 0; q < 4; ++q) { v[q][0] = *(const f32x4*)(s + q * 64); v[q][1] = *(const f32x4*)(s + q * 64 + 4); } }
;     ...
;         __syncthreads();
;         { const int n = tid >> 3, k8 = (tid & 7) * 8;
; #pragma unroll
;           for (int q = 0; q < 4; ++q) {
;               const LAS unsigned* p = tl + (q * 64 + n) * 33 + (k8 >> 1);
;               u32x4 ww; ww.x = p[0]; ww.y = p[1]; ww.z = p[2]; ww.w = p[3];
;               const int cc = ct * 256 + q * 64 + n;
;               const int drow = d.mode == 0 ? d.doff + cc : ((cc >> 7) * 256 + (cc & 127) + (d.mode == 2 ? 128 : 0));
;               *(u32x4*)(d.dst + (size_t)drow * d.K + kt * 64 + k8) = ww; } }
;         __syncthreads();
;     }
; }
	s_cmpk_ge_u32 s0, 0x220
	s_cselect_b32 s34, 1, 0
	s_cmpk_ge_u32 s0, 0x120
	s_cselect_b32 s35, 1, 0
	s_cmpk_ge_u32 s0, 0xc0
	s_cselect_b32 s41, 1, 0
	s_mul_i32 s36, s41, 0xc0
	s_mul_i32 s39, s35, 0x60
	s_add_i32 s36, s36, s39
	s_lshl_b32 s39, s34, 8
	s_add_i32 s36, s36, s39
	s_sub_i32 s36, s0, s36
	s_sub_i32 s41, s41, s35
	s_mul_hi_u32 s37, s36, 0x15555556
	s_mul_i32 s38, s37, 12
	s_sub_i32 s38, s36, s38
	s_lshr_b32 s39, s36, 5
	s_and_b32 s40, s36, 31
	s_cmp_eq_u32 s34, 1
	s_cselect_b32 s37, s37, s39
	s_cselect_b32 s38, s38, s40
	s_mov_b32 s59, 0x40000
	s_cselect_b32 s59, 0x18000, s59
	s_mov_b32 s90, 0x80000
	s_cselect_b32 s90, 0x30000, s90
	s_mov_b32 s33, 0xc0000
	s_cselect_b32 s33, 0x48000, s33
	s_mov_b32 s39, 0x1000
	s_cselect_b32 s39, 0x600, s39
	s_cselect_b64 s[28:29], -1, 0
	s_add_u32 s56, s22, 0x1500000
	s_addc_u32 s57, s23, 0
	s_cmp_eq_u32 s34, 1
	s_cselect_b32 s56, s56, s50
	s_cselect_b32 s57, s57, s51
	s_sub_i32 s40, s35, s34
	s_cmp_eq_u32 s40, 1
	s_cselect_b32 s56, s52, s56
	s_cselect_b32 s57, s53, s57
	s_lshl_b32 s40, s37, 8
	s_mul_i32 s36, s41, 0x600
	s_add_i32 s40, s40, s36
	s_mul_i32 s40, s40, s39
	s_lshl_b32 s36, s38, 7
	s_add_u32 s40, s40, s36
	s_add_u32 s56, s56, s40
	s_addc_u32 s57, s57, 0
	v_cndmask_b32_e64 v107, v104, v105, s[28:29]
	v_add_u32_e32 v108, s59, v107
	v_add_u32_e32 v109, s90, v107
	v_add_u32_e32 v110, s33, v107
	ds_read_b32 v80, v103 offset:33792
	ds_read_b32 v81, v103 offset:33796
	ds_read_b32 v82, v103 offset:33800
	ds_read_b32 v83, v103 offset:33804
	ds_read_b32 v84, v103 offset:42240
	ds_read_b32 v85, v103 offset:42244
	ds_read_b32 v86, v103 offset:42248
	ds_read_b32 v87, v103 offset:42252
	ds_read_b32 v88, v103 offset:50688
	ds_read_b32 v89, v103 offset:50692
	ds_read_b32 v90, v103 offset:50696
	ds_read_b32 v91, v103 offset:50700
	ds_read_b32 v92, v103 offset:59136
	ds_read_b32 v93, v103 offset:59140
	ds_read_b32 v94, v103 offset:59144
	ds_read_b32 v95, v103 offset:59148
	s_waitcnt lgkmcnt(0)
	global_store_dwordx4 v107, v[80:83], s[56:57]
	global_store_dwordx4 v108, v[84:87], s[56:57]
	global_store_dwordx4 v109, v[88:91], s[56:57]
	global_store_dwordx4 v110, v[92:95], s[56:57]
	s_add_i32 s0, s0, s2
	s_cmp_lt_u32 s0, 580
	s_cbranch_scc1 .Latr_loop
.Latr_done:
	s_waitcnt vmcnt(0)
	v_readlane_b32 s0, v255, 24
	v_readlane_b32 s2, v255, 25
	v_readlane_b32 s28, v255, 26
	v_readlane_b32 s29, v255, 27
	v_readlane_b32 s33, v255, 28
	v_readlane_b32 s34, v255, 29
	v_readlane_b32 s35, v255, 30
	v_readlane_b32 s36, v255, 31
	v_readlane_b32 s37, v255, 32
	v_readlane_b32 s38, v255, 33
	v_readlane_b32 s39, v255, 34
	v_readlane_b32 s40, v255, 35
	v_readlane_b32 s41, v255, 36
	v_readlane_b32 s44, v255, 37
	v_readlane_b32 s45, v255, 38
	v_readlane_b32 s46, v255, 39
	v_readlane_b32 s47, v255, 44
	v_readlane_b32 s48, v255, 45
	v_readlane_b32 s49, v255, 46
	v_readlane_b32 s50, v255, 47
	v_readlane_b32 s51, v255, 48
	v_readlane_b32 s52, v255, 49
	v_readlane_b32 s53, v255, 50
	v_readlane_b32 s54, v255, 51
	v_readlane_b32 s55, v255, 52
	v_readlane_b32 s56, v255, 53
	v_readlane_b32 s57, v255, 54
	v_readlane_b32 s58, v255, 55
	v_readlane_b32 s59, v255, 56
	v_readlane_b32 s90, v255, 57
	v_readlane_b32 vcc_lo, v255, 58
	v_readlane_b32 vcc_hi, v255, 59
	s_nop 3
	v_readlane_b32 s4, v253, 4
	s_mul_i32 s0, s30, 0x1600000
	v_readlane_b32 s10, v253, 10
	v_readlane_b32 s11, v253, 11
	s_add_u32 s50, s10, s0
	s_addc_u32 s51, s11, 0
	v_mov_b32_e32 v32, v175
	s_cmpk_lt_i32 s48, 0
	v_lshlrev_b32_e32 v0, 3, v32
	v_and_b32_e32 v34, 56, v0
	v_mov_b32_e32 v0, 0
	s_cselect_b64 s[28:29], -1, 0
	v_ashrrev_i32_e32 v35, 3, v32
	s_and_b64 vcc, exec, s[28:29]
	v_mov_b32_e32 v1, v0
	v_mov_b32_e32 v2, v0
	v_mov_b32_e32 v3, v0
	v_mov_b32_e32 v4, v0
	v_mov_b32_e32 v5, v0
	v_mov_b32_e32 v6, v0
	v_mov_b32_e32 v7, v0
	v_mov_b32_e32 v8, v0
	v_mov_b32_e32 v9, v0
	v_mov_b32_e32 v10, v0
	v_mov_b32_e32 v11, v0
	v_mov_b32_e32 v12, v0
	v_mov_b32_e32 v13, v0
	v_mov_b32_e32 v14, v0
	v_mov_b32_e32 v15, v0
	v_mov_b32_e32 v16, v0
	v_mov_b32_e32 v17, v0
	v_mov_b32_e32 v18, v0
	v_mov_b32_e32 v19, v0
	v_mov_b32_e32 v20, v0
	v_mov_b32_e32 v21, v0
	v_mov_b32_e32 v22, v0
	v_mov_b32_e32 v23, v0
	v_mov_b32_e32 v24, v0
	v_mov_b32_e32 v25, v0
	v_mov_b32_e32 v26, v0
	v_mov_b32_e32 v27, v0
	v_mov_b32_e32 v28, v0
	v_mov_b32_e32 v29, v0
	v_mov_b32_e32 v30, v0
	v_mov_b32_e32 v31, v0
	v_readlane_b32 s5, v253, 5
	v_readlane_b32 s6, v253, 6
	v_readlane_b32 s7, v253, 7
	v_readlane_b32 s8, v253, 8
	v_readlane_b32 s9, v253, 9
	v_readlane_b32 s12, v253, 12
	v_readlane_b32 s13, v253, 13
	v_readlane_b32 s14, v253, 14
	v_readlane_b32 s15, v253, 15
	v_readlane_b32 s16, v253, 16
	v_readlane_b32 s17, v253, 17
	v_readlane_b32 s18, v253, 18
	v_readlane_b32 s19, v253, 19
	s_cbranch_vccz .LBB0_83
	s_ashr_i32 s0, s48, 31
	s_lshr_b32 s0, s0, 27
	s_add_i32 s0, s48, s0
	s_and_b32 s2, s0, 0x3ffffe0
	s_sub_i32 s2, s48, s2
	v_lshl_add_u32 v2, s2, 6, v35
	v_mov_b64_e32 v[0:1], s[50:51]
	v_mad_i64_i32 v[0:1], s[34:35], v2, s3, v[0:1]
	s_lshl_b32 s0, s0, 3
	s_and_b32 s34, s0, 0xffffff00
	s_ashr_i32 s35, s34, 31
	v_lshl_add_u64 v[0:1], s[34:35], 2, v[0:1]
	v_lshlrev_b32_e32 v172, 2, v34
	v_lshl_add_u64 v[28:29], v[0:1], 0, v[172:173]
	global_load_dwordx4 v[0:3], v[28:29], off
	global_load_dwordx4 v[4:7], v[28:29], off offset:16
	global_load_dwordx4 v[8:11], v[28:29], off offset:256
	global_load_dwordx4 v[12:15], v[28:29], off offset:272
	global_load_dwordx4 v[16:19], v[28:29], off offset:512
	global_load_dwordx4 v[20:23], v[28:29], off offset:528
	global_load_dwordx4 v[24:27], v[28:29], off offset:768
	s_nop 0
	global_load_dwordx4 v[28:31], v[28:29], off offset:784

; template <class SEL, class CTX>
; __device__ __forceinline__ void transpose_run(LAS unsigned char* lds, const CTX& ctx, int t0, int t1, int stride) {
;     ...
;     if (t0 < t1) { SEL::get(ctx, t0, d, lt); const int nkt = d.K >> 6, kt = lt % nkt, ct = lt / nkt;
;         const float* s = d.src + (size_t)(kt * 64 + k) * d.ldsrc + d.c0 + ct * 256 + n8;
; #pragma unroll
;         for (int q = 0; q < 4; ++q) { v[q][0] = *(const f32x4*)(s + q * 64); v[q][1] = *(const f32x4*)(s + q * 64 + 4); } }
.LBB0_152:
	v_mov_b32_e32 v32, v175
	s_waitcnt vmcnt(0)
	v_mov_b32_e32 v16, 0
	v_lshlrev_b32_e32 v0, 3, v32
	s_cmpk_lt_i32 s48, 0
	v_ashrrev_i32_e32 v35, 3, v32
	v_and_b32_e32 v34, 56, v0
	s_cselect_b64 s[28:29], -1, 0
	s_cmpk_gt_i32 s48, -1
	v_mov_b32_e32 v17, v16
	v_mov_b32_e32 v18, v16
	v_mov_b32_e32 v19, v16
	v_mov_b32_e32 v0, v16
	v_mov_b32_e32 v1, v16
	v_mov_b32_e32 v2, v16
	v_mov_b32_e32 v3, v16
	v_mov_b32_e32 v4, v16
	v_mov_b32_e32 v5, v16
	v_mov_b32_e32 v6, v16
	v_mov_b32_e32 v7, v16
	v_mov_b32_e32 v8, v16
	v_mov_b32_e32 v9, v16
	v_mov_b32_e32 v10, v16
	v_mov_b32_e32 v11, v16
	v_mov_b32_e32 v12, v16
	v_mov_b32_e32 v13, v16
	v_mov_b32_e32 v14, v16
	v_mov_b32_e32 v15, v16
	v_mov_b32_e32 v20, v16
	v_mov_b32_e32 v21, v16
	v_mov_b32_e32 v22, v16
	v_mov_b32_e32 v23, v16
	v_mov_b32_e32 v24, v16
	v_mov_b32_e32 v25, v16
	v_mov_b32_e32 v26, v16
	v_mov_b32_e32 v27, v16
	v_mov_b32_e32 v28, v16
	v_mov_b32_e32 v29, v16
	v_mov_b32_e32 v30, v16
	v_mov_b32_e32 v31, v16
	s_cbranch_scc1 .LBB0_154
	s_ashr_i32 s0, s48, 31
	s_lshr_b32 s0, s0, 27
	s_add_i32 s0, s48, s0
	s_and_b32 s2, s0, 0x3ffffe0
	s_sub_i32 s2, s48, s2
	v_lshl_add_u32 v2, s2, 6, v35
	v_mov_b64_e32 v[0:1], s[50:51]
	v_mad_i64_i32 v[0:1], s[34:35], v2, s3, v[0:1]
	s_lshl_b32 s0, s0, 3
	s_and_b32 s34, s0, 0xffffff00
	s_ashr_i32 s35, s34, 31
	v_lshl_add_u64 v[0:1], s[34:35], 2, v[0:1]
	v_lshlrev_b32_e32 v172, 2, v34
	v_lshl_add_u64 v[0:1], v[0:1], 0, v[172:173]
	v_add_co_u32_e32 v16, vcc, s56, v0
	v_lshl_add_u64 v[28:29], v[0:1], 0, s[4:5]
	s_nop 0
	v_addc_co_u32_e32 v17, vcc, 0, v1, vcc
	global_load_dwordx4 v[0:3], v[28:29], off offset:16
	global_load_dwordx4 v[4:7], v[28:29], off offset:256
	global_load_dwordx4 v[8:11], v[28:29], off offset:272
	global_load_dwordx4 v[12:15], v[28:29], off offset:512
	global_load_dwordx4 v[20:23], v[28:29], off offset:528
	global_load_dwordx4 v[24:27], v[28:29], off offset:768
	s_nop 0
	global_load_dwordx4 v[16:19], v[16:17], off
	s_nop 0
	global_load_dwordx4 v[28:31], v[28:29], off offset:784

; template <class SEL, class CTX>
; __device__ __forceinline__ void transpose_run(LAS unsigned char* lds, const CTX& ctx, int t0, int t1, int stride) {
;     ...
;     if (t0 < t1) { SEL::get(ctx, t0, d, lt); const int nkt = d.K >> 6, kt = lt % nkt, ct = lt / nkt;
;         const float* s = d.src + (size_t)(kt * 64 + k) * d.ldsrc + d.c0 + ct * 256 + n8;
; #pragma unroll
;         for (int q = 0; q < 4; ++q) { v[q][0] = *(const f32x4*)(s + q * 64); v[q][1] = *(const f32x4*)(s + q * 64 + 4); } }
.LBB0_223:
	s_mov_b32 s31, s91
	v_readlane_b32 s52, v253, 20
	s_lshl_b64 s[28:29], s[30:31], 24
	v_readlane_b32 s56, v253, 24
	v_readlane_b32 s57, v253, 25
	s_add_u32 s28, s56, s28
	v_mov_b32_e32 v32, v175
	s_addc_u32 s29, s57, s29
	s_cmpk_lt_i32 s48, 0
	s_waitcnt vmcnt(0)
	v_lshlrev_b32_e32 v0, 3, v32
	v_and_b32_e32 v34, 56, v0
	v_mov_b32_e32 v0, 0
	v_ashrrev_i32_e32 v35, 3, v32
	s_cselect_b64 s[34:35], -1, 0
	s_cmpk_gt_i32 s48, -1
	v_mov_b32_e32 v1, v0
	v_mov_b32_e32 v2, v0
	v_mov_b32_e32 v3, v0
	v_mov_b32_e32 v4, v0
	v_mov_b32_e32 v5, v0
	v_mov_b32_e32 v6, v0
	v_mov_b32_e32 v7, v0
	v_mov_b32_e32 v8, v0
	v_mov_b32_e32 v9, v0
	v_mov_b32_e32 v10, v0
	v_mov_b32_e32 v11, v0
	v_mov_b32_e32 v12, v0
	v_mov_b32_e32 v13, v0
	v_mov_b32_e32 v14, v0
	v_mov_b32_e32 v15, v0
	v_mov_b32_e32 v16, v0
	v_mov_b32_e32 v17, v0
	v_mov_b32_e32 v18, v0
	v_mov_b32_e32 v19, v0
	v_mov_b32_e32 v20, v0
	v_mov_b32_e32 v21, v0
	v_mov_b32_e32 v22, v0
	v_mov_b32_e32 v23, v0
	v_mov_b32_e32 v24, v0
	v_mov_b32_e32 v25, v0
	v_mov_b32_e32 v26, v0
	v_mov_b32_e32 v27, v0
	v_mov_b32_e32 v28, v0
	v_mov_b32_e32 v29, v0
	v_mov_b32_e32 v30, v0
	v_mov_b32_e32 v31, v0
	v_readlane_b32 s53, v253, 21
	v_readlane_b32 s54, v253, 22
	v_readlane_b32 s55, v253, 23
	v_readlane_b32 s58, v253, 26
	v_readlane_b32 s59, v253, 27
	v_readlane_b32 s60, v253, 28
	v_readlane_b32 s61, v253, 29
	v_readlane_b32 s62, v253, 30
	v_readlane_b32 s63, v253, 31
	v_readlane_b32 s64, v253, 32
	v_readlane_b32 s65, v253, 33
	v_readlane_b32 s66, v253, 34
	v_readlane_b32 s67, v253, 35
	s_cbranch_scc1 .LBB0_225
	s_ashr_i32 s0, s48, 31
	s_lshr_b32 s0, s0, 27
	s_add_i32 s0, s48, s0
	s_and_b32 s2, s0, 0x3ffffe0
	s_sub_i32 s2, s48, s2
	v_lshl_add_u32 v0, s2, 6, v35
	v_ashrrev_i32_e32 v1, 31, v0
	s_lshl_b32 s0, s0, 3
	v_lshlrev_b64 v[0:1], 13, v[0:1]
	s_and_b32 s36, s0, 0xffffff00
	v_lshl_add_u64 v[0:1], s[28:29], 0, v[0:1]
	s_ashr_i32 s37, s36, 31
	v_lshl_add_u64 v[0:1], s[36:37], 2, v[0:1]
	v_lshlrev_b32_e32 v172, 2, v34
	v_lshl_add_u64 v[28:29], v[0:1], 0, v[172:173]
	global_load_dwordx4 v[0:3], v[28:29], off
	global_load_dwordx4 v[4:7], v[28:29], off offset:16
	global_load_dwordx4 v[8:11], v[28:29], off offset:256
	global_load_dwordx4 v[12:15], v[28:29], off offset:272
	global_load_dwordx4 v[16:19], v[28:29], off offset:512
	global_load_dwordx4 v[20:23], v[28:29], off offset:528
	global_load_dwordx4 v[24:27], v[28:29], off offset:768
	s_nop 0
	global_load_dwordx4 v[28:31], v[28:29], off offset:784

; template <class SEL, class CTX>
; __device__ __forceinline__ void transpose_run(LAS unsigned char* lds, const CTX& ctx, int t0, int t1, int stride) {
;     ...
;     if (t0 < t1) { SEL::get(ctx, t0, d, lt); const int nkt = d.K >> 6, kt = lt % nkt, ct = lt / nkt;
;         const float* s = d.src + (size_t)(kt * 64 + k) * d.ldsrc + d.c0 + ct * 256 + n8;
; #pragma unroll
;         for (int q = 0; q < 4; ++q) { v[q][0] = *(const f32x4*)(s + q * 64); v[q][1] = *(const f32x4*)(s + q * 64 + 4); } }
.LBB0_294:
	s_mul_i32 s0, s30, 0x240000
	s_add_u32 s28, s18, s0
	v_mov_b32_e32 v32, v175
	s_addc_u32 s29, s19, 0
	s_cmp_lt_i32 s48, 0
	s_waitcnt vmcnt(0)
	v_lshlrev_b32_e32 v0, 3, v32
	v_and_b32_e32 v34, 56, v0
	v_mov_b32_e32 v0, 0
	v_ashrrev_i32_e32 v35, 3, v32
	s_cselect_b64 s[34:35], -1, 0
	s_cmp_gt_i32 s48, -1
	v_mov_b32_e32 v1, v0
	v_mov_b32_e32 v2, v0
	v_mov_b32_e32 v3, v0
	v_mov_b32_e32 v4, v0
	v_mov_b32_e32 v5, v0
	v_mov_b32_e32 v6, v0
	v_mov_b32_e32 v7, v0
	v_mov_b32_e32 v8, v0
	v_mov_b32_e32 v9, v0
	v_mov_b32_e32 v10, v0
	v_mov_b32_e32 v11, v0
	v_mov_b32_e32 v12, v0
	v_mov_b32_e32 v13, v0
	v_mov_b32_e32 v14, v0
	v_mov_b32_e32 v15, v0
	v_mov_b32_e32 v16, v0
	v_mov_b32_e32 v17, v0
	v_mov_b32_e32 v18, v0
	v_mov_b32_e32 v19, v0
	v_mov_b32_e32 v20, v0
	v_mov_b32_e32 v21, v0
	v_mov_b32_e32 v22, v0
	v_mov_b32_e32 v23, v0
	v_mov_b32_e32 v24, v0
	v_mov_b32_e32 v25, v0
	v_mov_b32_e32 v26, v0
	v_mov_b32_e32 v27, v0
	v_mov_b32_e32 v28, v0
	v_mov_b32_e32 v29, v0
	v_mov_b32_e32 v30, v0
	v_mov_b32_e32 v31, v0
	s_cbranch_scc1 .LBB0_296
	s_mul_hi_i32 s0, s48, 0x2aaaaaab
	s_lshr_b32 s2, s0, 31
	s_ashr_i32 s0, s0, 1
	s_add_i32 s0, s0, s2
	s_mul_i32 s2, s0, 12
	s_sub_i32 s2, s48, s2
	v_lshl_add_u32 v2, s2, 6, v35
	v_mov_b64_e32 v[0:1], s[28:29]
	v_mad_i64_i32 v[0:1], s[36:37], v2, s88, v[0:1]
	s_lshl_b32 s36, s0, 8
	s_ashr_i32 s37, s36, 31
	v_lshl_add_u64 v[0:1], s[36:37], 2, v[0:1]
	v_lshlrev_b32_e32 v172, 2, v34
	v_lshl_add_u64 v[28:29], v[0:1], 0, v[172:173]
	global_load_dwordx4 v[0:3], v[28:29], off
	global_load_dwordx4 v[4:7], v[28:29], off offset:16
	global_load_dwordx4 v[8:11], v[28:29], off offset:256
	global_load_dwordx4 v[12:15], v[28:29], off offset:272
	global_load_dwordx4 v[16:19], v[28:29], off offset:512
	global_load_dwordx4 v[20:23], v[28:29], off offset:528
	global_load_dwordx4 v[24:27], v[28:29], off offset:768
	s_nop 0
	global_load_dwordx4 v[28:31], v[28:29], off offset:784
